# mixer queue: context-attention units fetch the next work id at the start of their epilogue (atomic hidden behind the epilogue)
# speedup vs baseline: 1.0093x; 1.0012x over previous
.LBB0_409:
	s_or_b64 exec, exec, s[0:1]
	s_mov_b32 s101, 0
	s_lshl_b32 s34, s97, 7
	s_lshl_b64 s[0:1], s[34:35], 2
	s_add_u32 s48, s14, s0
	s_addc_u32 s49, s15, s1
	s_lshl_b32 s2, s97, 8
	v_writelane_b32 v252, s2, 17
	s_lshl_b32 s3, s97, 9
	s_lshl_b32 s10, s97, 10
	v_writelane_b32 v252, s3, 18
	s_lshl_b32 s3, s97, 3
	s_add_u32 s6, s68, s0
	v_writelane_b32 v252, s3, 19
	s_addc_u32 s7, s69, s1
	v_writelane_b32 v252, s6, 20
	s_add_u32 s0, s70, s0
	s_addc_u32 s1, s71, s1
	v_writelane_b32 v252, s7, 21
	v_writelane_b32 v252, s0, 22
	s_mul_i32 s2, s97, 0x910000
	s_mul_i32 s4, s97, 0x4800
	v_writelane_b32 v252, s1, 23
	v_readlane_b32 s0, v253, 35
	s_add_u32 s0, s0, s2
	s_mov_b32 s5, s35
	v_writelane_b32 v252, s0, 24
	v_readlane_b32 s0, v253, 36
	s_addc_u32 s0, s0, 0
	s_mul_i32 s34, s97, 0x600
	v_writelane_b32 v252, s0, 25
	v_writelane_b32 v252, s4, 26
	s_add_u32 s11, s74, s4
	s_addc_u32 s96, s75, 0
	s_lshl_b64 s[0:1], s[34:35], 2
	s_add_u32 s84, s76, s0
	s_addc_u32 s85, s77, s1
	s_add_u32 s0, s14, s2
	s_addc_u32 s1, s15, 0
	v_writelane_b32 v252, s5, 27
	s_add_u32 s19, s0, 0xa108000
	s_addc_u32 s8, s1, 0
	v_writelane_b32 v252, s48, 28
	s_waitcnt lgkmcnt(0)
	s_barrier
	v_writelane_b32 v252, s49, 29
	s_branch .LBB0_413

.LBB0_413:
	v_mov_b32_e32 v130, v220
	s_nop 0
	v_cmp_eq_u32_e32 vcc, 0, v130
	s_barrier
	s_and_saveexec_b64 s[0:1], vcc
	s_cbranch_execz .LBB0_417
	s_mov_b64 s[4:5], exec
	v_mbcnt_lo_u32_b32 v1, s4, 0
	v_mbcnt_hi_u32_b32 v1, s5, v1
	v_cmp_eq_u32_e32 vcc, 0, v1
	s_and_saveexec_b64 s[2:3], vcc
	s_cbranch_execz .LBB0_416
	s_cmp_eq_u32 s101, 1
	s_cbranch_scc0 .Llq_dyn
	s_mov_b32 s101, 0
	s_waitcnt vmcnt(0)
	v_mov_b32_e32 v2, v255
	s_branch .LBB0_416
.Llq_dyn:
	s_bcnt1_i32_b64 s4, s[4:5]
	v_mov_b32_e32 v2, s4
	global_atomic_add v2, v0, v2, s[48:49] sc0

.LBB0_457:
	v_cmp_eq_u32_e32 vcc, 0, v220
	s_and_saveexec_b64 s[100:101], vcc
	s_cbranch_execz .Llq_a
	v_mov_b32_e32 v255, 1
	global_atomic_add v255, v0, v255, s[48:49] sc0
.Llq_a:
	s_mov_b64 exec, s[100:101]
	s_mov_b32 s101, 1
	ds_bpermute_b32 v1, v1, v156
	v_readlane_b32 s0, v254, 33
	v_lshlrev_b64 v[2:3], 12, v[128:129]
	v_readlane_b32 s1, v254, 34
	v_and_b32_e32 v4, 0xffff0000, v134
	s_waitcnt lgkmcnt(0)
	v_add_f32_e32 v5, v156, v1
	v_lshlrev_b32_e32 v1, 16, v134
	v_mul_f32_e32 v8, 0xbfb8aa3b, v1
	v_exp_f32_e32 v8, v8
	v_lshl_add_u64 v[2:3], s[0:1], 0, v[2:3]
	v_lshlrev_b32_e32 v6, 16, v135
	ds_bpermute_b32 v199, v125, v5
	v_add_f32_e32 v8, 1.0, v8
	v_div_scale_f32 v9, s[0:1], v8, v8, v1
	v_rcp_f32_e32 v10, v9
	v_and_b32_e32 v7, 0xffff0000, v135
	s_lshl_b32 s34, s4, 1
	v_lshl_add_u64 v[2:3], v[2:3], 0, s[34:35]
	v_fma_f32 v11, -v9, v10, 1.0
	v_fmac_f32_e32 v10, v11, v10
	v_div_scale_f32 v11, vcc, v1, v8, v1
	v_mul_f32_e32 v12, v11, v10
	v_fma_f32 v13, -v9, v12, v11
	v_fmac_f32_e32 v12, v13, v10
	v_fma_f32 v9, -v9, v12, v11
	v_div_fmas_f32 v9, v9, v10, v12
	v_div_fixup_f32 v8, v9, v8, v1
	v_mul_f32_e32 v1, 0xbfb8aa3b, v4
	v_exp_f32_e32 v1, v1
	s_nop 0
	v_add_f32_e32 v1, 1.0, v1
	v_div_scale_f32 v9, s[0:1], v1, v1, v4
	v_rcp_f32_e32 v10, v9
	s_nop 0
	v_fma_f32 v11, -v9, v10, 1.0
	v_fmac_f32_e32 v10, v11, v10
	v_div_scale_f32 v11, vcc, v4, v1, v4
	v_mul_f32_e32 v12, v11, v10
	v_fma_f32 v13, -v9, v12, v11
	v_fmac_f32_e32 v12, v13, v10
	v_fma_f32 v9, -v9, v12, v11
	v_div_fmas_f32 v9, v9, v10, v12
	v_div_fixup_f32 v9, v9, v1, v4
	v_mul_f32_e32 v1, 0xbfb8aa3b, v6
	v_exp_f32_e32 v4, v1
	s_waitcnt lgkmcnt(0)
	v_pk_add_f32 v[4:5], v[4:5], v[198:199]
	s_nop 0
	v_div_scale_f32 v1, s[0:1], v4, v4, v6
	v_rcp_f32_e32 v10, v1
	s_nop 0
	v_fma_f32 v11, -v1, v10, 1.0
	v_fmac_f32_e32 v10, v11, v10
	v_div_scale_f32 v11, vcc, v6, v4, v6
	v_mul_f32_e32 v12, v11, v10
	v_fma_f32 v13, -v1, v12, v11
	v_fmac_f32_e32 v12, v13, v10
	v_fma_f32 v1, -v1, v12, v11
	v_div_fmas_f32 v1, v1, v10, v12
	v_div_fixup_f32 v6, v1, v4, v6
	v_div_scale_f32 v1, s[0:1], v5, v5, 1.0
	v_rcp_f32_e32 v4, v1
	s_nop 0
	v_fma_f32 v10, -v1, v4, 1.0
	v_fmac_f32_e32 v4, v10, v4
	v_div_scale_f32 v10, vcc, 1.0, v5, 1.0
	v_mul_f32_e32 v11, v10, v4
	v_fma_f32 v12, -v1, v11, v10
	v_fmac_f32_e32 v11, v12, v4
	v_fma_f32 v1, -v1, v11, v10
	v_div_fmas_f32 v1, v1, v4, v11
	v_div_fixup_f32 v1, v1, v5, 1.0
	v_mul_f32_e32 v4, v94, v1
	v_mul_f32_e32 v4, v8, v4
	v_mul_f32_e32 v8, 0xbfb8aa3b, v7
	v_exp_f32_e32 v8, v8
	v_mul_f32_e32 v5, v95, v1
	v_mul_f32_e32 v5, v9, v5
	v_cvt_pk_bf16_f32 v4, v4, v5
	v_add_f32_e32 v8, 1.0, v8
	v_div_scale_f32 v9, s[0:1], v8, v8, v7
	v_rcp_f32_e32 v10, v9
	v_mul_f32_e32 v5, v96, v1
	v_mul_f32_e32 v5, v6, v5
	v_mul_f32_e32 v6, v97, v1
	v_fma_f32 v11, -v9, v10, 1.0
	v_fmac_f32_e32 v10, v11, v10
	v_div_scale_f32 v11, vcc, v7, v8, v7
	v_mul_f32_e32 v12, v11, v10
	v_fma_f32 v13, -v9, v12, v11
	v_fmac_f32_e32 v12, v13, v10
	v_fma_f32 v9, -v9, v12, v11
	v_div_fmas_f32 v9, v9, v10, v12
	v_div_fixup_f32 v7, v9, v8, v7
	v_mul_f32_e32 v6, v7, v6
	v_cvt_pk_bf16_f32 v5, v5, v6
	v_lshlrev_b32_e32 v6, 1, v124
	v_mov_b32_e32 v7, v0
	v_lshl_add_u64 v[2:3], v[2:3], 0, v[6:7]
	global_store_dwordx2 v[2:3], v[4:5], off
	v_lshlrev_b32_e32 v4, 16, v132
	v_mul_f32_e32 v9, 0xbfb8aa3b, v4
	v_exp_f32_e32 v9, v9
	v_and_b32_e32 v5, 0xffff0000, v132
	v_mul_f32_e32 v8, v90, v1
	v_lshlrev_b32_e32 v6, 16, v133
	v_add_f32_e32 v9, 1.0, v9
	v_div_scale_f32 v10, s[0:1], v9, v9, v4
	v_rcp_f32_e32 v11, v10
	v_and_b32_e32 v7, 0xffff0000, v133
	v_fma_f32 v12, -v10, v11, 1.0
	v_fmac_f32_e32 v11, v12, v11
	v_div_scale_f32 v12, vcc, v4, v9, v4
	v_mul_f32_e32 v13, v12, v11
	v_fma_f32 v14, -v10, v13, v12
	v_fmac_f32_e32 v13, v14, v11
	v_fma_f32 v10, -v10, v13, v12
	v_div_fmas_f32 v10, v10, v11, v13
	v_div_fixup_f32 v4, v10, v9, v4
	v_mul_f32_e32 v9, 0xbfb8aa3b, v5
	v_exp_f32_e32 v9, v9
	v_mul_f32_e32 v4, v4, v8
	v_mul_f32_e32 v8, v91, v1
	v_add_f32_e32 v9, 1.0, v9
	v_div_scale_f32 v10, s[0:1], v9, v9, v5
	v_rcp_f32_e32 v11, v10
	s_nop 0
	v_fma_f32 v12, -v10, v11, 1.0
	v_fmac_f32_e32 v11, v12, v11
	v_div_scale_f32 v12, vcc, v5, v9, v5
	v_mul_f32_e32 v13, v12, v11
	v_fma_f32 v14, -v10, v13, v12
	v_fmac_f32_e32 v13, v14, v11
	v_fma_f32 v10, -v10, v13, v12
	v_div_fmas_f32 v10, v10, v11, v13
	v_div_fixup_f32 v5, v10, v9, v5
	v_mul_f32_e32 v5, v5, v8
	v_mul_f32_e32 v8, 0xbfb8aa3b, v6
	v_exp_f32_e32 v8, v8
	v_cvt_pk_bf16_f32 v4, v4, v5
	v_mul_f32_e32 v5, v92, v1
	v_add_f32_e32 v8, 1.0, v8
	v_div_scale_f32 v9, s[0:1], v8, v8, v6
	v_rcp_f32_e32 v10, v9
	s_nop 0
	v_fma_f32 v11, -v9, v10, 1.0
	v_fmac_f32_e32 v10, v11, v10
	v_div_scale_f32 v11, vcc, v6, v8, v6
	v_mul_f32_e32 v12, v11, v10
	v_fma_f32 v13, -v9, v12, v11
	v_fmac_f32_e32 v12, v13, v10
	v_fma_f32 v9, -v9, v12, v11
	v_div_fmas_f32 v9, v9, v10, v12
	v_div_fixup_f32 v6, v9, v8, v6
	v_mul_f32_e32 v8, 0xbfb8aa3b, v7
	v_exp_f32_e32 v8, v8
	v_mul_f32_e32 v5, v6, v5
	v_mul_f32_e32 v6, v93, v1
	v_add_f32_e32 v8, 1.0, v8
	v_div_scale_f32 v9, s[0:1], v8, v8, v7
	v_rcp_f32_e32 v10, v9
	s_nop 0
	v_fma_f32 v11, -v9, v10, 1.0
	v_fmac_f32_e32 v10, v11, v10
	v_div_scale_f32 v11, vcc, v7, v8, v7
	v_mul_f32_e32 v12, v11, v10
	v_fma_f32 v13, -v9, v12, v11
	v_fmac_f32_e32 v12, v13, v10
	v_fma_f32 v9, -v9, v12, v11
	v_div_fmas_f32 v9, v9, v10, v12
	v_div_fixup_f32 v7, v9, v8, v7
	v_mul_f32_e32 v6, v7, v6
	v_cvt_pk_bf16_f32 v5, v5, v6
	global_store_dwordx2 v[2:3], v[4:5], off offset:32
	v_lshlrev_b32_e32 v4, 16, v126
	v_mul_f32_e32 v9, 0xbfb8aa3b, v4
	v_exp_f32_e32 v9, v9
	v_and_b32_e32 v5, 0xffff0000, v126
	v_mul_f32_e32 v8, v86, v1
	v_lshlrev_b32_e32 v6, 16, v127
	v_add_f32_e32 v9, 1.0, v9
	v_div_scale_f32 v10, s[0:1], v9, v9, v4
	v_rcp_f32_e32 v11, v10
	v_and_b32_e32 v7, 0xffff0000, v127
	v_fma_f32 v12, -v10, v11, 1.0
	v_fmac_f32_e32 v11, v12, v11
	v_div_scale_f32 v12, vcc, v4, v9, v4
	v_mul_f32_e32 v13, v12, v11
	v_fma_f32 v14, -v10, v13, v12
	v_fmac_f32_e32 v13, v14, v11
	v_fma_f32 v10, -v10, v13, v12
	v_div_fmas_f32 v10, v10, v11, v13
	v_div_fixup_f32 v4, v10, v9, v4
	v_mul_f32_e32 v9, 0xbfb8aa3b, v5
	v_exp_f32_e32 v9, v9
	v_mul_f32_e32 v4, v4, v8
	v_mul_f32_e32 v8, v87, v1
	v_add_f32_e32 v9, 1.0, v9
	v_div_scale_f32 v10, s[0:1], v9, v9, v5
	v_rcp_f32_e32 v11, v10
	s_nop 0
	v_fma_f32 v12, -v10, v11, 1.0
	v_fmac_f32_e32 v11, v12, v11
	v_div_scale_f32 v12, vcc, v5, v9, v5
	v_mul_f32_e32 v13, v12, v11
	v_fma_f32 v14, -v10, v13, v12
	v_fmac_f32_e32 v13, v14, v11
	v_fma_f32 v10, -v10, v13, v12
	v_div_fmas_f32 v10, v10, v11, v13
	v_div_fixup_f32 v5, v10, v9, v5
	v_mul_f32_e32 v5, v5, v8
	v_mul_f32_e32 v8, 0xbfb8aa3b, v6
	v_exp_f32_e32 v8, v8
	v_cvt_pk_bf16_f32 v4, v4, v5
	v_mul_f32_e32 v5, v88, v1
	v_add_f32_e32 v8, 1.0, v8
	v_div_scale_f32 v9, s[0:1], v8, v8, v6
	v_rcp_f32_e32 v10, v9
	s_nop 0
	v_fma_f32 v11, -v9, v10, 1.0
	v_fmac_f32_e32 v10, v11, v10
	v_div_scale_f32 v11, vcc, v6, v8, v6
	v_mul_f32_e32 v12, v11, v10
	v_fma_f32 v13, -v9, v12, v11
	v_fmac_f32_e32 v12, v13, v10
	v_fma_f32 v9, -v9, v12, v11
	v_div_fmas_f32 v9, v9, v10, v12
	v_div_fixup_f32 v6, v9, v8, v6
	v_mul_f32_e32 v8, 0xbfb8aa3b, v7
	v_exp_f32_e32 v8, v8
	v_mul_f32_e32 v5, v6, v5
	v_mul_f32_e32 v6, v89, v1
	v_add_f32_e32 v8, 1.0, v8
	v_div_scale_f32 v9, s[0:1], v8, v8, v7
	v_rcp_f32_e32 v10, v9
	s_nop 0
	v_fma_f32 v11, -v9, v10, 1.0
	v_fmac_f32_e32 v10, v11, v10
	v_div_scale_f32 v11, vcc, v7, v8, v7
	v_mul_f32_e32 v12, v11, v10
	v_fma_f32 v13, -v9, v12, v11
	v_fmac_f32_e32 v12, v13, v10
	v_fma_f32 v9, -v9, v12, v11
	v_div_fmas_f32 v9, v9, v10, v12
	v_div_fixup_f32 v7, v9, v8, v7
	v_mul_f32_e32 v6, v7, v6
	v_cvt_pk_bf16_f32 v5, v5, v6
	global_store_dwordx2 v[2:3], v[4:5], off offset:64
	v_lshlrev_b32_e32 v4, 16, v122
	v_mul_f32_e32 v9, 0xbfb8aa3b, v4
	v_exp_f32_e32 v9, v9
	v_and_b32_e32 v5, 0xffff0000, v122
	v_mul_f32_e32 v8, v82, v1
	v_lshlrev_b32_e32 v6, 16, v123
	v_add_f32_e32 v9, 1.0, v9
	v_div_scale_f32 v10, s[0:1], v9, v9, v4
	v_rcp_f32_e32 v11, v10
	v_and_b32_e32 v7, 0xffff0000, v123
	v_fma_f32 v12, -v10, v11, 1.0
	v_fmac_f32_e32 v11, v12, v11
	v_div_scale_f32 v12, vcc, v4, v9, v4
	v_mul_f32_e32 v13, v12, v11
	v_fma_f32 v14, -v10, v13, v12
	v_fmac_f32_e32 v13, v14, v11
	v_fma_f32 v10, -v10, v13, v12
	v_div_fmas_f32 v10, v10, v11, v13
	v_div_fixup_f32 v4, v10, v9, v4
	v_mul_f32_e32 v9, 0xbfb8aa3b, v5
	v_exp_f32_e32 v9, v9
	v_mul_f32_e32 v4, v4, v8
	v_mul_f32_e32 v8, v83, v1
	v_add_f32_e32 v9, 1.0, v9
	v_div_scale_f32 v10, s[0:1], v9, v9, v5
	v_rcp_f32_e32 v11, v10
	s_nop 0
	v_fma_f32 v12, -v10, v11, 1.0
	v_fmac_f32_e32 v11, v12, v11
	v_div_scale_f32 v12, vcc, v5, v9, v5
	v_mul_f32_e32 v13, v12, v11
	v_fma_f32 v14, -v10, v13, v12
	v_fmac_f32_e32 v13, v14, v11
	v_fma_f32 v10, -v10, v13, v12
	v_div_fmas_f32 v10, v10, v11, v13
	v_div_fixup_f32 v5, v10, v9, v5
	v_mul_f32_e32 v5, v5, v8
	v_mul_f32_e32 v8, 0xbfb8aa3b, v6
	v_exp_f32_e32 v8, v8
	v_cvt_pk_bf16_f32 v4, v4, v5
	v_mul_f32_e32 v5, v84, v1
	v_add_f32_e32 v8, 1.0, v8
	v_div_scale_f32 v9, s[0:1], v8, v8, v6
	v_rcp_f32_e32 v10, v9
	s_nop 0
	v_fma_f32 v11, -v9, v10, 1.0
	v_fmac_f32_e32 v10, v11, v10
	v_div_scale_f32 v11, vcc, v6, v8, v6
	v_mul_f32_e32 v12, v11, v10
	v_fma_f32 v13, -v9, v12, v11
	v_fmac_f32_e32 v12, v13, v10
	v_fma_f32 v9, -v9, v12, v11
	v_div_fmas_f32 v9, v9, v10, v12
	v_div_fixup_f32 v6, v9, v8, v6
	v_mul_f32_e32 v8, 0xbfb8aa3b, v7
	v_exp_f32_e32 v8, v8
	v_mul_f32_e32 v5, v6, v5
	v_mul_f32_e32 v6, v85, v1
	v_add_f32_e32 v8, 1.0, v8
	v_div_scale_f32 v9, s[0:1], v8, v8, v7
	v_rcp_f32_e32 v10, v9
	s_nop 0
	v_fma_f32 v11, -v9, v10, 1.0
	v_fmac_f32_e32 v10, v11, v10
	v_div_scale_f32 v11, vcc, v7, v8, v7
	v_mul_f32_e32 v12, v11, v10
	v_fma_f32 v13, -v9, v12, v11
	v_fmac_f32_e32 v12, v13, v10
	v_fma_f32 v9, -v9, v12, v11
	v_div_fmas_f32 v9, v9, v10, v12
	v_div_fixup_f32 v7, v9, v8, v7
	v_mul_f32_e32 v6, v7, v6
	v_cvt_pk_bf16_f32 v5, v5, v6
	global_store_dwordx2 v[2:3], v[4:5], off offset:96
	v_lshlrev_b32_e32 v4, 16, v120
	v_mul_f32_e32 v9, 0xbfb8aa3b, v4
	v_exp_f32_e32 v9, v9
	v_and_b32_e32 v5, 0xffff0000, v120
	v_mul_f32_e32 v8, v78, v1
	v_lshlrev_b32_e32 v6, 16, v121
	v_add_f32_e32 v9, 1.0, v9
	v_div_scale_f32 v10, s[0:1], v9, v9, v4
	v_rcp_f32_e32 v11, v10
	v_and_b32_e32 v7, 0xffff0000, v121
	v_fma_f32 v12, -v10, v11, 1.0
	v_fmac_f32_e32 v11, v12, v11
	v_div_scale_f32 v12, vcc, v4, v9, v4
	v_mul_f32_e32 v13, v12, v11
	v_fma_f32 v14, -v10, v13, v12
	v_fmac_f32_e32 v13, v14, v11
	v_fma_f32 v10, -v10, v13, v12
	v_div_fmas_f32 v10, v10, v11, v13
	v_div_fixup_f32 v4, v10, v9, v4
	v_mul_f32_e32 v9, 0xbfb8aa3b, v5
	v_exp_f32_e32 v9, v9
	v_mul_f32_e32 v4, v4, v8
	v_mul_f32_e32 v8, v79, v1
	v_add_f32_e32 v9, 1.0, v9
	v_div_scale_f32 v10, s[0:1], v9, v9, v5
	v_rcp_f32_e32 v11, v10
	s_nop 0
	v_fma_f32 v12, -v10, v11, 1.0
	v_fmac_f32_e32 v11, v12, v11
	v_div_scale_f32 v12, vcc, v5, v9, v5
	v_mul_f32_e32 v13, v12, v11
	v_fma_f32 v14, -v10, v13, v12
	v_fmac_f32_e32 v13, v14, v11
	v_fma_f32 v10, -v10, v13, v12
	v_div_fmas_f32 v10, v10, v11, v13
	v_div_fixup_f32 v5, v10, v9, v5
	v_mul_f32_e32 v5, v5, v8
	v_mul_f32_e32 v8, 0xbfb8aa3b, v6
	v_exp_f32_e32 v8, v8
	v_cvt_pk_bf16_f32 v4, v4, v5
	v_mul_f32_e32 v5, v80, v1
	v_add_f32_e32 v8, 1.0, v8
	v_div_scale_f32 v9, s[0:1], v8, v8, v6
	v_rcp_f32_e32 v10, v9
	s_nop 0
	v_fma_f32 v11, -v9, v10, 1.0
	v_fmac_f32_e32 v10, v11, v10
	v_div_scale_f32 v11, vcc, v6, v8, v6
	v_mul_f32_e32 v12, v11, v10
	v_fma_f32 v13, -v9, v12, v11
	v_fmac_f32_e32 v12, v13, v10
	v_fma_f32 v9, -v9, v12, v11
	v_div_fmas_f32 v9, v9, v10, v12
	v_div_fixup_f32 v6, v9, v8, v6
	v_mul_f32_e32 v8, 0xbfb8aa3b, v7
	v_exp_f32_e32 v8, v8
	v_mul_f32_e32 v5, v6, v5
	v_mul_f32_e32 v6, v81, v1
	v_add_f32_e32 v8, 1.0, v8
	v_div_scale_f32 v9, s[0:1], v8, v8, v7
	v_rcp_f32_e32 v10, v9
	s_nop 0
	v_fma_f32 v11, -v9, v10, 1.0
	v_fmac_f32_e32 v10, v11, v10
	v_div_scale_f32 v11, vcc, v7, v8, v7
	v_mul_f32_e32 v12, v11, v10
	v_fma_f32 v13, -v9, v12, v11
	v_fmac_f32_e32 v12, v13, v10
	v_fma_f32 v9, -v9, v12, v11
	v_div_fmas_f32 v9, v9, v10, v12
	v_div_fixup_f32 v7, v9, v8, v7
	v_mul_f32_e32 v6, v7, v6
	v_cvt_pk_bf16_f32 v5, v5, v6
	global_store_dwordx2 v[2:3], v[4:5], off offset:128
	v_lshlrev_b32_e32 v4, 16, v118
	v_mul_f32_e32 v9, 0xbfb8aa3b, v4
	v_exp_f32_e32 v9, v9
	v_and_b32_e32 v5, 0xffff0000, v118
	v_mul_f32_e32 v8, v62, v1
	v_lshlrev_b32_e32 v6, 16, v119
	v_add_f32_e32 v9, 1.0, v9
	v_div_scale_f32 v10, s[0:1], v9, v9, v4
	v_rcp_f32_e32 v11, v10
	v_and_b32_e32 v7, 0xffff0000, v119
	v_fma_f32 v12, -v10, v11, 1.0
	v_fmac_f32_e32 v11, v12, v11
	v_div_scale_f32 v12, vcc, v4, v9, v4
	v_mul_f32_e32 v13, v12, v11
	v_fma_f32 v14, -v10, v13, v12
	v_fmac_f32_e32 v13, v14, v11
	v_fma_f32 v10, -v10, v13, v12
	v_div_fmas_f32 v10, v10, v11, v13
	v_div_fixup_f32 v4, v10, v9, v4
	v_mul_f32_e32 v9, 0xbfb8aa3b, v5
	v_exp_f32_e32 v9, v9
	v_mul_f32_e32 v4, v4, v8
	v_mul_f32_e32 v8, v63, v1
	v_add_f32_e32 v9, 1.0, v9
	v_div_scale_f32 v10, s[0:1], v9, v9, v5
	v_rcp_f32_e32 v11, v10
	s_nop 0
	v_fma_f32 v12, -v10, v11, 1.0
	v_fmac_f32_e32 v11, v12, v11
	v_div_scale_f32 v12, vcc, v5, v9, v5
	v_mul_f32_e32 v13, v12, v11
	v_fma_f32 v14, -v10, v13, v12
	v_fmac_f32_e32 v13, v14, v11
	v_fma_f32 v10, -v10, v13, v12
	v_div_fmas_f32 v10, v10, v11, v13
	v_div_fixup_f32 v5, v10, v9, v5
	v_mul_f32_e32 v5, v5, v8
	v_mul_f32_e32 v8, 0xbfb8aa3b, v6
	v_exp_f32_e32 v8, v8
	v_cvt_pk_bf16_f32 v4, v4, v5
	v_mul_f32_e32 v5, v64, v1
	v_add_f32_e32 v8, 1.0, v8
	v_div_scale_f32 v9, s[0:1], v8, v8, v6
	v_rcp_f32_e32 v10, v9
	s_nop 0
	v_fma_f32 v11, -v9, v10, 1.0
	v_fmac_f32_e32 v10, v11, v10
	v_div_scale_f32 v11, vcc, v6, v8, v6
	v_mul_f32_e32 v12, v11, v10
	v_fma_f32 v13, -v9, v12, v11
	v_fmac_f32_e32 v12, v13, v10
	v_fma_f32 v9, -v9, v12, v11
	v_div_fmas_f32 v9, v9, v10, v12
	v_div_fixup_f32 v6, v9, v8, v6
	v_mul_f32_e32 v8, 0xbfb8aa3b, v7
	v_exp_f32_e32 v8, v8
	v_mul_f32_e32 v5, v6, v5
	v_mul_f32_e32 v6, v65, v1
	v_add_f32_e32 v8, 1.0, v8
	v_div_scale_f32 v9, s[0:1], v8, v8, v7
	v_rcp_f32_e32 v10, v9
	s_nop 0
	v_fma_f32 v11, -v9, v10, 1.0
	v_fmac_f32_e32 v10, v11, v10
	v_div_scale_f32 v11, vcc, v7, v8, v7
	v_mul_f32_e32 v12, v11, v10
	v_fma_f32 v13, -v9, v12, v11
	v_fmac_f32_e32 v12, v13, v10
	v_fma_f32 v9, -v9, v12, v11
	v_div_fmas_f32 v9, v9, v10, v12
	v_div_fixup_f32 v7, v9, v8, v7
	v_mul_f32_e32 v6, v7, v6
	v_cvt_pk_bf16_f32 v5, v5, v6
	global_store_dwordx2 v[2:3], v[4:5], off offset:160
	v_lshlrev_b32_e32 v4, 16, v116
	v_mul_f32_e32 v9, 0xbfb8aa3b, v4
	v_exp_f32_e32 v9, v9
	v_and_b32_e32 v5, 0xffff0000, v116
	v_mul_f32_e32 v8, v54, v1
	v_lshlrev_b32_e32 v6, 16, v117
	v_add_f32_e32 v9, 1.0, v9
	v_div_scale_f32 v10, s[0:1], v9, v9, v4
	v_rcp_f32_e32 v11, v10
	v_and_b32_e32 v7, 0xffff0000, v117
	v_fma_f32 v12, -v10, v11, 1.0
	v_fmac_f32_e32 v11, v12, v11
	v_div_scale_f32 v12, vcc, v4, v9, v4
	v_mul_f32_e32 v13, v12, v11
	v_fma_f32 v14, -v10, v13, v12
	v_fmac_f32_e32 v13, v14, v11
	v_fma_f32 v10, -v10, v13, v12
	v_div_fmas_f32 v10, v10, v11, v13
	v_div_fixup_f32 v4, v10, v9, v4
	v_mul_f32_e32 v9, 0xbfb8aa3b, v5
	v_exp_f32_e32 v9, v9
	v_mul_f32_e32 v4, v4, v8
	v_mul_f32_e32 v8, v55, v1
	v_add_f32_e32 v9, 1.0, v9
	v_div_scale_f32 v10, s[0:1], v9, v9, v5
	v_rcp_f32_e32 v11, v10
	s_nop 0
	v_fma_f32 v12, -v10, v11, 1.0
	v_fmac_f32_e32 v11, v12, v11
	v_div_scale_f32 v12, vcc, v5, v9, v5
	v_mul_f32_e32 v13, v12, v11
	v_fma_f32 v14, -v10, v13, v12
	v_fmac_f32_e32 v13, v14, v11
	v_fma_f32 v10, -v10, v13, v12
	v_div_fmas_f32 v10, v10, v11, v13
	v_div_fixup_f32 v5, v10, v9, v5
	v_mul_f32_e32 v5, v5, v8
	v_mul_f32_e32 v8, 0xbfb8aa3b, v6
	v_exp_f32_e32 v8, v8
	v_cvt_pk_bf16_f32 v4, v4, v5
	v_mul_f32_e32 v5, v56, v1
	v_add_f32_e32 v8, 1.0, v8
	v_div_scale_f32 v9, s[0:1], v8, v8, v6
	v_rcp_f32_e32 v10, v9
	s_nop 0
	v_fma_f32 v11, -v9, v10, 1.0
	v_fmac_f32_e32 v10, v11, v10
	v_div_scale_f32 v11, vcc, v6, v8, v6
	v_mul_f32_e32 v12, v11, v10
	v_fma_f32 v13, -v9, v12, v11
	v_fmac_f32_e32 v12, v13, v10
	v_fma_f32 v9, -v9, v12, v11
	v_div_fmas_f32 v9, v9, v10, v12
	v_div_fixup_f32 v6, v9, v8, v6
	v_mul_f32_e32 v8, 0xbfb8aa3b, v7
	v_exp_f32_e32 v8, v8
	v_mul_f32_e32 v5, v6, v5
	v_mul_f32_e32 v6, v57, v1
	v_add_f32_e32 v8, 1.0, v8
	v_div_scale_f32 v9, s[0:1], v8, v8, v7
	v_rcp_f32_e32 v10, v9
	s_nop 0
	v_fma_f32 v11, -v9, v10, 1.0
	v_fmac_f32_e32 v10, v11, v10
	v_div_scale_f32 v11, vcc, v7, v8, v7
	v_mul_f32_e32 v12, v11, v10
	v_fma_f32 v13, -v9, v12, v11
	v_fmac_f32_e32 v12, v13, v10
	v_fma_f32 v9, -v9, v12, v11
	v_div_fmas_f32 v9, v9, v10, v12
	v_div_fixup_f32 v7, v9, v8, v7
	v_mul_f32_e32 v6, v7, v6
	v_cvt_pk_bf16_f32 v5, v5, v6
	global_store_dwordx2 v[2:3], v[4:5], off offset:192
	v_lshlrev_b32_e32 v4, 16, v114
	v_mul_f32_e32 v9, 0xbfb8aa3b, v4
	v_exp_f32_e32 v9, v9
	v_and_b32_e32 v5, 0xffff0000, v114
	v_mul_f32_e32 v8, v50, v1
	v_lshlrev_b32_e32 v6, 16, v115
	v_add_f32_e32 v9, 1.0, v9
	v_div_scale_f32 v10, s[0:1], v9, v9, v4
	v_rcp_f32_e32 v11, v10
	v_and_b32_e32 v7, 0xffff0000, v115
	v_fma_f32 v12, -v10, v11, 1.0
	v_fmac_f32_e32 v11, v12, v11
	v_div_scale_f32 v12, vcc, v4, v9, v4
	v_mul_f32_e32 v13, v12, v11
	v_fma_f32 v14, -v10, v13, v12
	v_fmac_f32_e32 v13, v14, v11
	v_fma_f32 v10, -v10, v13, v12
	v_div_fmas_f32 v10, v10, v11, v13
	v_div_fixup_f32 v4, v10, v9, v4
	v_mul_f32_e32 v9, 0xbfb8aa3b, v5
	v_exp_f32_e32 v9, v9
	v_mul_f32_e32 v4, v4, v8
	v_mul_f32_e32 v8, v51, v1
	v_add_f32_e32 v9, 1.0, v9
	v_div_scale_f32 v10, s[0:1], v9, v9, v5
	v_rcp_f32_e32 v11, v10
	s_nop 0
	v_fma_f32 v12, -v10, v11, 1.0
	v_fmac_f32_e32 v11, v12, v11
	v_div_scale_f32 v12, vcc, v5, v9, v5
	v_mul_f32_e32 v13, v12, v11
	v_fma_f32 v14, -v10, v13, v12
	v_fmac_f32_e32 v13, v14, v11
	v_fma_f32 v10, -v10, v13, v12
	v_div_fmas_f32 v10, v10, v11, v13
	v_div_fixup_f32 v5, v10, v9, v5
	v_mul_f32_e32 v5, v5, v8
	v_mul_f32_e32 v8, 0xbfb8aa3b, v6
	v_exp_f32_e32 v8, v8
	v_cvt_pk_bf16_f32 v4, v4, v5
	v_mul_f32_e32 v5, v52, v1
	v_mul_f32_e32 v1, v53, v1
	v_add_f32_e32 v8, 1.0, v8
	v_div_scale_f32 v9, s[0:1], v8, v8, v6
	v_rcp_f32_e32 v10, v9
	s_nop 0
	v_fma_f32 v11, -v9, v10, 1.0
	v_fmac_f32_e32 v10, v11, v10
	v_div_scale_f32 v11, vcc, v6, v8, v6
	v_mul_f32_e32 v12, v11, v10
	v_fma_f32 v13, -v9, v12, v11
	v_fmac_f32_e32 v12, v13, v10
	v_fma_f32 v9, -v9, v12, v11
	v_div_fmas_f32 v9, v9, v10, v12
	v_div_fixup_f32 v6, v9, v8, v6
	v_mul_f32_e32 v5, v6, v5
	v_mul_f32_e32 v6, 0xbfb8aa3b, v7
	v_exp_f32_e32 v6, v6
	s_nop 0
	v_add_f32_e32 v6, 1.0, v6
	v_div_scale_f32 v8, s[0:1], v6, v6, v7
	v_rcp_f32_e32 v9, v8
	s_nop 0
	v_fma_f32 v10, -v8, v9, 1.0
	v_fmac_f32_e32 v9, v10, v9
	v_div_scale_f32 v10, vcc, v7, v6, v7
	v_mul_f32_e32 v11, v10, v9
	v_fma_f32 v12, -v8, v11, v10
	v_fmac_f32_e32 v11, v12, v9
	v_fma_f32 v8, -v8, v11, v10
	v_div_fmas_f32 v8, v8, v9, v11
	v_div_fixup_f32 v6, v8, v6, v7
	v_mul_f32_e32 v1, v6, v1
	v_cvt_pk_bf16_f32 v5, v5, v1
	global_store_dwordx2 v[2:3], v[4:5], off offset:224
